# P3 attention waves: skip the mid-step vmcnt(0) for st>0 (q already resident; it waited for this step's row DMAs) and end-of-step wait vmcnt(1) (not the store just issued); plus earlier edits
# speedup vs baseline: 1.0038x; 1.0038x over previous
; __device__ __forceinline__ unsigned cvt_pk(float lo, float hi) { f32x2_t v = {lo, hi}; bf16x2_t b = __builtin_convertvector(v, bf16x2_t); return __builtin_bit_cast(unsigned, b); }
; __device__ __forceinline__ size_t blk_off(int row, int col, int K) { return ((size_t)((row >> 8) * (K >> 6) + (col >> 6)) << 14) + (size_t)(((row & 255) << 6) + (col & 63)); }
; __global__ void __launch_bounds__(NWAVES * 64, 2) fwd(Args a) {
;     ...
;                     lsum = red_sum_16_32(lsum);
;                     const float il = 1.0f / lsum;
; #pragma unroll
;                     for (int pr = 0; pr < 2; ++pr) {
;                         unsigned ex = cvt_pk(oacc[2 * pr][0] * il, oacc[2 * pr][1] * il), ey = cvt_pk(oacc[2 * pr][2] * il, oacc[2 * pr][3] * il);
;                         unsigned ox = cvt_pk(oacc[2 * pr + 1][0] * il, oacc[2 * pr + 1][1] * il), oy = cvt_pk(oacc[2 * pr + 1][2] * il, oacc[2 * pr + 1][3] * il);
;                         asm volatile("s_nop 1\n\tv_permlane16_swap_b32 %0, %1" : "+v"(ex), "+v"(ox)); asm volatile("s_nop 1\n\tv_permlane16_swap_b32 %0, %1" : "+v"(ey), "+v"(oy));
;                         v4u w; w.x = ex; w.y = ey; w.z = ox; w.w = oy;
;                         *(v4u*)(CATg + blk_off(qrow - GROWS * grp, h * 64 + 16 * (2 * pr + (fq & 1)) + 4 * (fq & ~1), D)) = w; }
.LBB0_260:
	v_mov_b32_e32 v2, v114
	s_nop 1
	v_permlane16_swap_b32 v114, v2
	s_add_i32 s28, s58, s87
	v_add_f32_e32 v2, v114, v2
	v_mov_b32_e32 v6, v2
	s_nop 1
	v_permlane32_swap_b32 v2, v6
	s_ashr_i32 s28, s28, 4
	v_add_f32_e32 v2, v2, v6
	v_div_scale_f32 v6, s[56:57], v2, v2, 1.0
	v_rcp_f32_e32 v7, v6
	v_div_scale_f32 v8, vcc, 1.0, v2, 1.0
	s_and_b32 s28, s28, -16
	v_fma_f32 v9, -v6, v7, 1.0
	v_fmac_f32_e32 v7, v9, v7
	v_mul_f32_e32 v9, v8, v7
	v_fma_f32 v10, -v6, v9, v8
	v_fmac_f32_e32 v9, v10, v7
	v_fma_f32 v6, -v6, v9, v8
	v_div_fmas_f32 v6, v6, v7, v9
	v_div_fixup_f32 v2, v6, v2, 1.0
	s_add_i32 s56, s28, s52
	s_ashr_i32 s57, s56, 31
	v_pk_mul_f32 v[6:7], v[2:3], v[102:103] op_sel_hi:[0,1]
	v_pk_mul_f32 v[8:9], v[2:3], v[104:105] op_sel_hi:[0,1]
	s_lshl_b64 s[56:57], s[56:57], 15
	v_cvt_pk_bf16_f32 v6, v6, v7
	v_cvt_pk_bf16_f32 v7, v8, v9
	v_pk_mul_f32 v[8:9], v[2:3], v[110:111] op_sel_hi:[0,1]
	v_pk_mul_f32 v[10:11], v[2:3], v[112:113] op_sel_hi:[0,1]
	s_add_u32 s56, s2, s56
	v_cvt_pk_bf16_f32 v8, v8, v9
	v_cvt_pk_bf16_f32 v9, v10, v11
	v_and_or_b32 v10, v141, s63, v189
	s_addc_u32 s57, s3, s57
	s_nop 1
	v_permlane16_swap_b32 v6, v8
	s_nop 1
	v_permlane16_swap_b32 v7, v9
	v_lshlrev_b32_e32 v12, 1, v10
	global_store_dwordx4 v12, v[6:9], s[56:57]
	v_pk_mul_f32 v[10:11], v[2:3], v[108:109] op_sel_hi:[0,1]
	s_waitcnt vmcnt(1)
	v_mov_b64_e32 v[66:67], v[86:87]
	v_pk_mul_f32 v[6:7], v[2:3], v[98:99] op_sel_hi:[0,1]
	v_pk_mul_f32 v[8:9], v[2:3], v[100:101] op_sel_hi:[0,1]
	v_cvt_pk_bf16_f32 v6, v6, v7
	v_cvt_pk_bf16_f32 v7, v8, v9
	v_pk_mul_f32 v[8:9], v[2:3], v[106:107] op_sel_hi:[0,1]
	v_cvt_pk_bf16_f32 v8, v8, v9
	v_cvt_pk_bf16_f32 v9, v10, v11
	s_nop 1
	v_permlane16_swap_b32 v6, v8
	s_nop 1
	v_permlane16_swap_b32 v7, v9
	global_store_dwordx4 v12, v[6:9], s[56:57] offset:64
	v_mov_b64_e32 v[70:71], v[82:83]
	v_mov_b32_e32 v81, v97
	v_mov_b64_e32 v[6:7], v[34:35]
	v_mov_b32_e32 v80, v96
	v_mov_b32_e32 v79, v95
	v_mov_b32_e32 v78, v94
	v_mov_b32_e32 v77, v93
	v_mov_b32_e32 v76, v92
	v_mov_b32_e32 v75, v91
	v_mov_b32_e32 v74, v90
	v_mov_b32_e32 v194, v147
	v_mov_b64_e32 v[8:9], v[36:37]
	v_mov_b64_e32 v[10:11], v[38:39]
	v_mov_b64_e32 v[12:13], v[40:41]
	v_mov_b64_e32 v[14:15], v[42:43]
	v_mov_b64_e32 v[16:17], v[44:45]
	v_mov_b64_e32 v[18:19], v[46:47]
	v_mov_b64_e32 v[20:21], v[48:49]
	v_mov_b64_e32 v[22:23], v[50:51]
	v_mov_b64_e32 v[24:25], v[52:53]
	v_mov_b64_e32 v[26:27], v[54:55]
	v_mov_b64_e32 v[28:29], v[56:57]
	v_mov_b64_e32 v[30:31], v[58:59]
	v_mov_b64_e32 v[32:33], v[60:61]
	v_mov_b64_e32 v[68:69], v[88:89]
	v_mov_b64_e32 v[72:73], v[84:85]
	v_mov_b64_e32 v[34:35], v[62:63]
	v_mov_b64_e32 v[36:37], v[64:65]

; #define LAS __attribute__((address_space(3)))
; #define AT_LDK(KF, RSX, i) do { const LAS unsigned char* kb_ = lds + KRING_OFF + (((RSX) + (i)) % 9) * 8192 + kc0 * 128; \
;                         _Pragma("unroll") for (int cbk = 0; cbk < 2; ++cbk) { KF[cbk][0] = *(const LAS bf16x8*)(kb_ + cbk * 2048 + koff0); KF[cbk][1] = *(const LAS bf16x8*)(kb_ + cbk * 2048 + koff1); } } while (0)
; #define AT_MF(KF) do { _Pragma("unroll") for (int cbk = 0; cbk < 2; ++cbk) { cq[cbk] = (f32x4){0.f, 0.f, 0.f, 0.f}; \
;                         cq[cbk] = __builtin_amdgcn_mfma_f32_16x16x32_bf16(KF[cbk][0], qfn[0], cq[cbk], 0, 0, 0); cq[cbk] = __builtin_amdgcn_mfma_f32_16x16x32_bf16(KF[cbk][1], qfn[1], cq[cbk], 0, 0, 0); } } while (0)
; #define AT_SC(RK, BS, i) do { f32x4 s_; _Pragma("unroll") for (int e = 0; e < 4; ++e) s_[e] = (sel[e] ? cq[1][e] : cq[0][e]) * (sel[e] ? RK[1][e] : RK[0][e]) + BS[e]; \
;                         sc[i] = s_; mxn = fmaxf(fmaxf(mxn, fmaxf(s_[0], s_[1])), fmaxf(s_[2], s_[3])); } while (0)
; __global__ void __launch_bounds__(NWAVES * 64, 2) fwd(Args a) {
;     ...
;                     AT_LDK(kA, rs, 7); AT_LDRB(rkvA, bsvA, rs, tba, 7); __builtin_amdgcn_sched_barrier(0);
;                     AT_MF(kA); __builtin_amdgcn_sched_barrier(0); AT_SC(rkvA, bsvA, 7); __builtin_amdgcn_sched_barrier(0);
;                     float mx = red_max_16_32(mxn);
;                     float lsum = 0.f;
;                     f32x4 oacc[4];
; #pragma unroll
;                     for (int db = 0; db < 4; ++db) oacc[db] = (f32x4){0.f, 0.f, 0.f, 0.f};
;                     s16x4 vaA[4], vbA[4];
;     ...
;                     if (st < 15) {
;                         const int rsn_ = min(max(r + 1 - 4, 0), rows - 8), dr0n = rsn_ - (r + 1) + 7;
;                         const LAS unsigned char* tbn[4];
; #pragma unroll
;                         for (int e = 0; e < 4; ++e) tbn[e] = (const LAS unsigned char*)(tbl + dr0n * 32) + dsel[e];
;                         AT_BUILDQ(qfn, qraw, qss); mxn = -3e38f;
;                         if (st < 14) { qss = hss[(size_t)h * MT + qrow + 128]; qraw[0] = *(const v4u*)(PROJg + (size_t)(qrow + 128 - GROWS * grp) * INW + h * 64 + 8 * fq); qraw[1] = *(const v4u*)(PROJg + (size_t)(qrow + 128 - GROWS * grp) * INW + h * 64 + 32 + 8 * fq); }
.LBB0_377:
	s_add_i32 s28, s41, 7
	s_mul_hi_u32 s70, s28, 0x38e38e39
	s_lshr_b32 s70, s70, 1
	s_mul_i32 s70, s70, 9
	s_sub_i32 s70, s28, s70
	s_lshl_b32 s28, s70, 13
	s_add_i32 s71, s89, s28
	v_add_u32_e32 v37, s71, v169
	v_add_u32_e32 v50, s71, v170
	ds_read_b128 v[38:41], v37
	ds_read_b128 v[42:45], v37 offset:2048
	ds_read_b128 v[46:49], v50
	ds_read_b128 v[50:53], v50 offset:2048
	v_lshl_add_u32 v37, s70, 8, v175
	ds_read_b128 v[54:57], v37
	ds_read_b128 v[58:61], v37 offset:64
	ds_read_b32 v125, v2 offset:1852
	ds_read_b32 v124, v34 offset:1852
	ds_read_b32 v123, v35 offset:1852
	ds_read_b32 v122, v36 offset:1852
	s_waitcnt lgkmcnt(0)
	v_mfma_f32_16x16x32_bf16 v[34:37], v[38:41], v[74:77], 0
	v_mfma_f32_16x16x32_bf16 v[38:41], v[42:45], v[74:77], 0
	v_mfma_f32_16x16x32_bf16 v[34:37], v[46:49], v[78:81], v[34:37]
	v_mfma_f32_16x16x32_bf16 v[38:41], v[50:53], v[78:81], v[38:41]
	s_nop 7
	v_cndmask_b32_e64 v2, v34, v38, s[4:5]
	v_cndmask_b32_e64 v34, v54, v58, s[4:5]
	v_fmac_f32_e32 v125, v2, v34
	v_cndmask_b32_e64 v2, v35, v39, s[6:7]
	v_cndmask_b32_e64 v34, v55, v59, s[6:7]
	v_fmac_f32_e32 v124, v2, v34
	v_cndmask_b32_e64 v2, v36, v40, s[8:9]
	v_cndmask_b32_e64 v34, v56, v60, s[8:9]
	v_fmac_f32_e32 v123, v2, v34
	v_cndmask_b32_e64 v2, v37, v41, s[10:11]
	v_cndmask_b32_e64 v34, v57, v61, s[10:11]
	v_fmac_f32_e32 v122, v2, v34
	v_max_f32_e32 v2, v125, v124
	v_max_f32_e32 v34, v123, v122
	v_max3_f32 v2, v195, v2, v34
	v_mov_b32_e32 v34, v2
	v_mov_b32_e32 v35, v2
	s_nop 1
	v_permlane16_swap_b32 v35, v34
	s_andn2_b64 vcc, exec, s[56:57]
	v_max_f32_e32 v34, v34, v34
	v_max_f32_e32 v35, v35, v35
	v_max_f32_e32 v34, v35, v34
	v_mov_b32_e32 v35, v34
	s_nop 1
	v_permlane32_swap_b32 v35, v34
	s_mov_b64 s[56:57], -1
	v_max_f32_e32 v34, v34, v34
	v_max_f32_e32 v35, v35, v35
	v_max_f32_e32 v146, v35, v34
	s_cbranch_vccnz .LBB0_381
	ds_read_b128 v[46:49], v92
	ds_read_b128 v[42:45], v92 offset:16
	ds_read_b128 v[38:41], v92 offset:128
	ds_read_b128 v[34:37], v92 offset:144
	s_cmp_lg_u32 s87, 0
	s_cbranch_scc1 .Lq_nowait
	s_waitcnt vmcnt(0)
.Lq_nowait:
	v_mov_b64_e32 v[84:85], v[72:73]
	v_mov_b64_e32 v[88:89], v[68:69]
	s_cmp_gt_u32 s40, 13
	v_mov_b64_e32 v[82:83], v[70:71]
	v_mov_b64_e32 v[86:87], v[66:67]
	v_mov_b32_e32 v147, v194
	s_cbranch_scc1 .LBB0_380
	v_add_u32_e32 v52, s87, v137
	v_add_u32_e32 v52, 0x80, v52
	v_ashrrev_i32_e32 v91, 31, v90
	v_ashrrev_i32_e32 v53, 31, v52
	v_lshl_add_u64 v[50:51], v[90:91], 2, s[54:55]
	v_lshlrev_b64 v[52:53], 12, v[52:53]
	v_lshl_add_u64 v[52:53], v[144:145], 0, v[52:53]
	global_load_dword v147, v[50:51], off offset:512
	global_load_dwordx4 v[82:85], v[52:53], off
	global_load_dwordx4 v[86:89], v[52:53], off offset:64
